# mixers queue: first item of a phase is the workgroup index (no atomic); later claims return counter + gridDim
# baseline (speedup 1.0000x reference)
_Z14fwd_megakernel6Params:
	v_and_b32_e32 v163, 0x3ff, v0
	v_writelane_b32 v254, s2, 0
	s_add_u32 s2, s0, 0x120
	s_addc_u32 s3, s1, 0
	v_writelane_b32 v254, s2, 1
	v_and_b32_e32 v0, 0x3fffffff, v0
	v_mbcnt_lo_u32_b32 v203, -1, 0
	v_writelane_b32 v254, s3, 2
	v_writelane_b32 v254, s0, 3
	v_mbcnt_hi_u32_b32 v204, -1, v203
	v_and_b32_e32 v205, 64, v204
	v_writelane_b32 v254, s1, 4
	s_load_dword s0, s[0:1], 0x120
	s_mov_b32 s1, 0
	s_movk_i32 s33, 0x6000
	v_mov_b32_e32 v1, 0
	v_mov_b32_e32 v162, 0x358637bd
	s_waitcnt lgkmcnt(0)
	v_writelane_b32 v254, s0, 5
	s_cmp_eq_u32 s0, 0x100
	s_cselect_b32 s2, 1, 0
	v_writelane_b32 v255, s2, 41
	s_mov_b32 s2, 0
	v_writelane_b32 v255, s2, 51
	v_writelane_b32 v255, s2, 52
	s_add_i32 s0, 0, 0x23fc0
	v_writelane_b32 v254, s0, 6
	s_add_i32 s0, 0, 0x19800
	v_writelane_b32 v254, s0, 7
	s_add_i32 s0, 0, 0x22400
	v_writelane_b32 v254, s0, 8
	s_add_i32 s0, 0, 0x22200
	v_writelane_b32 v254, s0, 9
	s_add_i32 s0, 0, 0x22000
	v_writelane_b32 v254, s0, 10
	s_add_i32 s0, 0, 0x11000
	v_writelane_b32 v254, s0, 11
	s_add_i32 s0, 0, 0x8800
	v_writelane_b32 v254, s0, 12
	s_add_i32 s0, 0, 0x225fc
	v_writelane_b32 v254, s0, 13
	s_add_i32 s0, 0, 0x221fc
	v_writelane_b32 v254, s0, 14
	s_add_i32 s0, 0, 0x23fe0
	v_writelane_b32 v254, s0, 15
	s_add_i32 s0, 0, 0x23fe4
	v_writelane_b32 v254, s0, 16
	s_mov_b32 s0, 0
	v_writelane_b32 v254, s0, 17
	v_writelane_b32 v254, s0, 18
	v_writelane_b32 v254, s0, 19
	s_mov_b32 s94, 0x30000
	v_mov_b32_e32 v171, 1
	v_writelane_b32 v254, s1, 20
	v_cmp_eq_u32_e64 s[0:1], 0, v0
	v_mov_b32_e32 v202, 0x2000
	v_add_u32_e32 v206, 64, v205
	v_writelane_b32 v254, s0, 21
	v_xor_b32_e32 v207, 32, v204
	v_xor_b32_e32 v208, 16, v204
	v_writelane_b32 v254, s1, 22
	s_mov_b64 s[0:1], 0
	v_writelane_b32 v254, s0, 23
	v_xor_b32_e32 v209, 8, v204
	v_xor_b32_e32 v220, 4, v204
	v_xor_b32_e32 v217, 2, v204
	v_xor_b32_e32 v212, 1, v204
	v_mov_b32_e32 v213, 0x7ff
	v_mov_b32_e32 v214, 0xff
	v_mov_b32_e32 v215, 0xffffff03
	v_mov_b64_e32 v[164:165], 0x17f
	v_mov_b64_e32 v[166:167], 0x180
	v_mov_b32_e32 v168, 0xff800000
	v_mov_b32_e32 v216, 0x800
	v_mov_b32_e32 v170, 0x3ecc95a3
	v_mov_b32_e32 v218, 0x7f800000
	v_mov_b32_e32 v219, 0x7fc00000
	v_mov_b32_e32 v221, 0x100
	v_mov_b32_e32 v222, 0x3f549a78
	v_mov_b32_e32 v223, 0x3fd49a78
	v_mov_b32_e32 v224, 0x42800000
	v_not_b32_e32 v225, 63
	v_not_b32_e32 v226, 31
	v_mov_b32_e32 v227, 0x6000
	v_mov_b32_e32 v228, 0x5000
	s_mov_b32 s95, 0x48000
	v_writelane_b32 v254, s1, 24
	s_mov_b64 s[92:93], 0x80
	s_branch .LBB0_3

.LBB0_534:
	s_and_b64 vcc, exec, s[4:5]
	s_cbranch_vccz .LBB0_704
	v_readlane_b32 s0, v254, 37
	s_mov_b64 s[4:5], -1
	s_cmp_gt_i32 s0, 1
	s_mov_b64 s[18:19], 0
	s_cbranch_scc0 .LBB0_906
	v_readlane_b32 s0, v254, 37
	s_cmp_gt_i32 s0, 2
	s_cbranch_scc0 .LBB0_705
	s_cmp_gt_i32 s0, 3
	s_cbranch_scc0 .LBB0_707
	v_readlane_b32 s2, v254, 25
	v_readlane_b32 s3, v254, 26
	s_load_dwordx2 s[2:3], s[2:3], 0x118
	v_readlane_b32 s0, v254, 29
	v_readlane_b32 s1, v254, 30
	s_mov_b32 s4, s0
	s_lshl_b32 s0, s0, 6
	s_ashr_i32 s1, s0, 31
	s_lshl_b64 s[0:1], s[0:1], 2
	s_waitcnt lgkmcnt(0)
	s_add_u32 s0, s2, s0
	s_addc_u32 s1, s3, s1
	v_writelane_b32 v254, s0, 40
	s_nop 1
	v_writelane_b32 v254, s1, 41
	s_mov_b32 s98, 1
	v_writelane_b32 v255, s98, 52
	s_add_u32 s0, s2, 0xcd54000
	v_writelane_b32 v254, s0, 42
	s_addc_u32 s0, s3, 0
	v_writelane_b32 v254, s0, 43
	s_add_u32 s0, s2, 0xdf54000
	v_writelane_b32 v254, s0, 44
	s_addc_u32 s0, s3, 0
	v_writelane_b32 v254, s0, 45
	s_add_u32 s0, s2, 0xcbb4000
	v_writelane_b32 v254, s0, 46
	s_addc_u32 s0, s3, 0
	v_writelane_b32 v254, s0, 47
	s_add_u32 s0, s2, 0xb134000
	v_writelane_b32 v254, s0, 48
	s_addc_u32 s0, s3, 0
	v_writelane_b32 v254, s0, 49
	s_add_u32 s0, s2, 0xcab4000
	v_writelane_b32 v254, s0, 50
	s_addc_u32 s0, s3, 0
	v_writelane_b32 v254, s0, 51
	s_add_u32 s0, s2, 0xcb34000
	v_writelane_b32 v254, s0, 52
	s_addc_u32 s0, s3, 0
	v_writelane_b32 v254, s0, 53
	s_mov_b32 s0, s4
	s_ashr_i32 s5, s4, 31
	v_writelane_b32 v254, s0, 29
	s_nop 1
	v_writelane_b32 v254, s1, 30
	s_lshl_b64 s[0:1], s[4:5], 1
	v_writelane_b32 v254, s0, 54
	s_nop 1
	v_writelane_b32 v254, s1, 55
	s_add_u32 s0, s2, 0x8134000
	s_addc_u32 s1, s3, 0
	v_writelane_b32 v254, s0, 56
	s_nop 1
	v_writelane_b32 v254, s1, 57
	s_add_u32 s0, s2, 0xc934000
	v_writelane_b32 v254, s0, 58
	s_addc_u32 s0, s3, 0
	v_writelane_b32 v254, s0, 59
	s_add_u32 s0, s2, 0x934000
	s_addc_u32 s1, s3, 0
	v_writelane_b32 v254, s0, 60
	s_nop 1
	v_writelane_b32 v254, s1, 61
	s_branch .LBB0_542

.LBB0_542:
	v_mov_b32_e32 v0, v163
	s_barrier
	s_nop 0
	v_cmp_eq_u32_e32 vcc, 0, v0
	s_and_saveexec_b64 s[4:5], vcc
	s_cbranch_execz .LBB0_546
	v_readlane_b32 s98, v255, 52
	s_cmp_eq_u32 s98, 0
	s_cbranch_scc1 .Lqs_later
	s_mov_b32 s98, 0
	v_writelane_b32 v255, s98, 52
	v_readlane_b32 s0, v254, 0
	s_branch .Lqs_have
.Lqs_later:
	v_readlane_b32 s98, v255, 51
	s_cmp_eq_u32 s98, 0
	s_cbranch_scc1 .Lqp_orig
	s_waitcnt vmcnt(0)
	v_readlane_b32 s0, v255, 50
	s_mov_b32 s98, 0
	v_writelane_b32 v255, s98, 51
	s_branch .Lqp_have

.Lqp_have:
	v_readlane_b32 s98, v254, 5
	s_nop 1
	s_add_i32 s0, s0, s98
